# FFN-chain phases handed over by 4-workgroup group barriers (same-XCD checked at run time) instead of grid barriers; norm/post/final rows remapped to the owning GEMM row-tile group; plus GEMM loop edit
# speedup vs baseline: 1.0076x; 1.0076x over previous
_Z10hybrid_fwd4Args:
	s_mov_b32 s32, 0
	v_cmp_eq_u32_e32 vcc, 0, v0
	s_and_saveexec_b64 s[4:5], vcc
	s_cbranch_execz .Lgc_e0
	s_load_dwordx2 s[8:9], s[0:1], 0xd8
	s_getreg_b32 s6, hwreg(HW_REG_XCC_ID, 0, 4)
	s_and_b32 s7, s2, 63
	s_lshl_b32 s7, s7, 8
	s_lshl_b32 s6, 1, s6
	s_waitcnt lgkmcnt(0)
	s_add_u32 s8, s8, s7
	s_addc_u32 s9, s9, 0
	s_add_u32 s8, s8, 0x10000
	s_addc_u32 s9, s9, 0
	v_mov_b32_e32 v248, 0
	v_mov_b32_e32 v249, s6
	global_atomic_or v248, v249, s[8:9] offset:4
.Lgc_e0:
	s_or_b64 exec, exec, s[4:5]
	s_mov_b32 s87, s2
	s_load_dwordx2 s[2:3], s[0:1], 0xe0
	v_cmp_gt_u32_e32 vcc, 8, v0
	s_waitcnt lgkmcnt(0)
	v_writelane_b32 v255, s2, 0
	s_nop 1
	v_writelane_b32 v255, s3, 1
	s_and_saveexec_b64 s[4:5], vcc
	v_lshl_add_u32 v1, v0, 2, 0
	v_add_u32_e32 v1, 0x20000, v1
	v_mov_b32_e32 v2, 0
	ds_write_b32 v1, v2
	s_or_b64 exec, exec, s[4:5]
	s_load_dwordx2 s[2:3], s[0:1], 0xe0
	s_waitcnt lgkmcnt(0)
	s_barrier
	s_sub_i32 s2, s3, s2
	s_cmp_gt_i32 s2, 1
	s_cbranch_scc1 .LBB0_4
	s_mov_b32 s90, 0
	v_cmp_eq_u32_e64 s[4:5], 0, v0
	s_cbranch_execz .LBB0_5
	s_branch .LBB0_9

.LBB0_47:
	s_or_b64 exec, exec, s[4:5]
	v_mov_b32_e32 v2, v0
	s_and_b32 s2, s87, 7
	s_lshl_b32 s2, s2, 5
	s_bfe_u32 s3, s87, 0x30003
	s_lshl_b32 s3, s3, 2
	s_or_b32 s2, s2, s3
	s_lshr_b32 s3, s87, 6
	s_and_b32 s3, s3, 3
	s_or_b32 s2, s2, s3
	s_lshl_b32 s2, s2, 3
	v_writelane_b32 v255, s2, 4
	s_lshl_b32 s3, s87, 3
	v_readfirstlane_b32 s2, v2
	s_ashr_i32 s14, s2, 6
	s_add_i32 s2, s14, s3
	s_cmp_lt_i32 s2, 0xb380
	s_cselect_b64 s[4:5], -1, 0
	s_cmp_gt_i32 s2, 0xb37f
	v_and_b32_e32 v4, 63, v2
	s_cbranch_scc1 .LBB0_53
	s_cmpk_lt_i32 s2, 0x2c00
	s_mov_b32 s15, s2
	s_cbranch_scc1 .LBB0_64
	s_cmpk_gt_u32 s2, 0x57ff
	s_cbranch_scc0 .LBB0_54
	s_cmpk_gt_u32 s2, 0x6dff
	s_cbranch_scc0 .LBB0_55
	s_cmpk_gt_u32 s2, 0x83ff
	s_cbranch_scc0 .LBB0_56
	s_add_i32 s15, s2, 0x8400
	s_mov_b64 s[6:7], 0
	s_branch .LBB0_57

.LBB0_256:
	v_cmp_eq_u32_e32 vcc, 0, v0
	s_and_saveexec_b64 s[4:5], vcc
	s_cbranch_execz .Lgc_e1
	s_load_dwordx2 s[8:9], s[0:1], 0xd8
	s_and_b32 s7, s87, 63
	s_lshl_b32 s7, s7, 8
	v_mov_b32_e32 v248, 0
	s_waitcnt lgkmcnt(0)
	s_add_u32 s10, s8, s7
	s_addc_u32 s11, s9, 0
	s_add_u32 s10, s10, 0x10000
	s_addc_u32 s11, s11, 0
	global_load_dword v250, v248, s[10:11] offset:4 sc1
	s_waitcnt vmcnt(0)
	v_readfirstlane_b32 s6, v250
	s_nop 3
	s_bcnt1_i32_b32 s6, s6
	s_cmp_lg_u32 s6, 1
	s_cselect_b32 s6, 1, 0
	s_cmp_lg_u32 s65, 0x100
	s_cselect_b32 s7, 1, 0
	s_or_b32 s6, s6, s7
	s_cmp_eq_u32 s6, 0
	s_cbranch_scc1 .Lgc_e1
	s_add_u32 s10, s8, 0x20000
	s_addc_u32 s11, s9, 0
	v_mov_b32_e32 v249, 1
	global_atomic_add v248, v249, s[10:11]
.Lgc_e1:
	s_or_b64 exec, exec, s[4:5]
	s_waitcnt lgkmcnt(0)
	s_abs_i32 s2, s65
	v_cvt_f32_u32_e32 v1, s2
	v_cmp_eq_u32_e64 s[4:5], 0, v0
	s_ashr_i32 s3, s65, 31
	s_mov_b32 s41, 0
	v_rcp_iflag_f32_e32 v1, v1
	v_writelane_b32 v255, s4, 5
	v_mov_b32_e32 v3, 0
	s_mov_b32 s91, 0xf800000
	v_mul_f32_e32 v1, 0x4f7ffffe, v1
	v_cvt_u32_f32_e32 v1, v1
	v_writelane_b32 v255, s5, 6
	s_sub_i32 s4, 0, s2
	v_mov_b32_e32 v214, 0x260
	v_readfirstlane_b32 s5, v1
	s_mul_i32 s4, s4, s5
	s_mul_hi_u32 s4, s5, s4
	s_add_i32 s5, s5, s4
	s_mul_hi_u32 s4, s5, 0x380
	s_mul_i32 s4, s4, s2
	s_sub_i32 s4, 0x380, s4
	s_sub_i32 s5, s4, s2
	s_cmp_ge_u32 s4, s2
	s_cselect_b32 s4, s5, s4
	s_sub_i32 s5, s4, s2
	s_cmp_ge_u32 s4, s2
	s_cselect_b32 s6, s5, s4
	s_and_b32 s2, s87, 7
	s_lshl_b32 s2, s2, 5
	s_bfe_u32 s4, s87, 0x30003
	s_lshl_b32 s4, s4, 2
	s_or_b32 s2, s2, s4
	s_lshr_b32 s4, s87, 6
	s_and_b32 s4, s4, 3
	s_or_b32 s2, s2, s4
	s_lshl_b32 s2, s2, 6
	s_sub_i32 s4, s65, s6
	v_writelane_b32 v255, s2, 7
	s_lshl_b32 s5, s6, 4
	s_lshl_b32 s4, s4, 3
	s_lshl_b32 s2, s65, 3
	v_writelane_b32 v255, s4, 8
	s_sub_i32 s4, s38, s5
	v_writelane_b32 v255, s4, 9
	s_sub_i32 s4, s2, s5
	s_addk_i32 s4, 0x5000
	v_writelane_b32 v255, s4, 10
	s_lshl_b32 s4, s6, 3
	v_writelane_b32 v255, s6, 11
	s_sub_i32 s2, s2, s4
	s_ashr_i32 s39, s38, 31
	v_writelane_b32 v255, s2, 12
	s_lshl_b64 s[4:5], s[38:39], 7
	v_writelane_b32 v255, s4, 13
	s_mov_b32 s2, 1
	s_add_i32 s6, 0, 0x20000
	v_writelane_b32 v255, s5, 14
	v_writelane_b32 v255, s2, 15
	v_writelane_b32 v255, s6, 16
	s_add_i32 s6, 0, 0x20004
	v_writelane_b32 v255, s6, 17
	s_add_i32 s6, 0, 0x14800
	v_writelane_b32 v255, s6, 18
	v_writelane_b32 v255, s87, 19
	s_lshl_b32 s88, s65, 6
	s_mov_b64 s[4:5], -1
	v_mov_b32_e32 v1, 0x358637bd
	s_mov_b32 s69, 0x800000
	s_mov_b32 s81, 0x1000000
	s_mov_b32 s33, 0x1800000
	s_brev_b32 s12, 64
	s_mov_b32 s13, 0x2800000
	s_mov_b32 s60, 0x3000000
	s_movk_i32 s89, 0x1000
	s_movk_i32 s2, 0x1fff
	s_mov_b64 s[50:51], 0x4000
	v_mov_b32_e32 v254, 1
	s_movk_i32 s42, 0x2000
	s_mov_b32 s92, 0x1ffffe0
	s_movk_i32 s80, 0x1c00
	s_mov_b32 s85, 0x5040100
	s_movk_i32 s43, 0x7fff
	s_movk_i32 s84, 0xc00
	s_mov_b32 s52, 0x42b504f3
	s_mov_b32 s53, 0x3d010000
	s_mov_b32 s54, 0x3ca10000
	s_mov_b32 s55, 0x3d018000
	s_mov_b32 s56, 0x3ca18000
	s_mov_b32 s57, 0x42ddb3d8
	v_mov_b64_e32 v[196:197], 0x200
	v_mov_b32_e32 v215, 0xbf317218
	v_mov_b32_e32 v218, 0xbfb8aa3b
	v_mov_b32_e32 v219, 0xf149f2ca
	v_mov_b32_e32 v220, 0xc0000
	s_mov_b64 s[62:63], 0x10000
	s_mov_b32 s64, 0x3e0293ee
	s_mov_b32 s68, 0x3dd53b94
	s_mov_b32 s66, s41
	s_mov_b32 s16, 0
	v_writelane_b32 v255, s90, 20
	s_branch .LBB0_258

.LBB0_284:
	v_readlane_b32 s4, v255, 15
	s_add_i32 s34, s4, 1
	v_readlane_b32 s4, v255, 0
	v_readlane_b32 s5, v255, 1
	s_cmp_ge_i32 s34, s5
	s_cbranch_scc1 .LBB0_338
	s_bitcmp0_b32 s32, 0
	s_cbranch_scc1 .Lgb0_slow
	s_waitcnt vmcnt(0)
	s_barrier
	s_add_i32 s32, s32, 16
	v_cmp_eq_u32_e32 vcc, 0, v0
	s_and_saveexec_b64 s[4:5], vcc
	s_cbranch_execz .Lgb0_join
	s_load_dwordx2 s[8:9], s[0:1], 0xd8
	s_and_b32 s11, s87, 63
	s_lshl_b32 s11, s11, 8
	v_mov_b32_e32 v248, 0
	v_mov_b32_e32 v249, 1
	s_mov_b32 s10, 0
	s_waitcnt lgkmcnt(0)
	s_add_u32 s8, s8, s11
	s_addc_u32 s9, s9, 0
	s_add_u32 s8, s8, 0x10000
	s_addc_u32 s9, s9, 0
	global_atomic_add v248, v249, s[8:9]
.Lgb0_spin:
	global_load_dword v250, v248, s[8:9] sc1
	s_waitcnt vmcnt(0)
	v_readfirstlane_b32 s11, v250
	s_nop 3
	s_lshl_b32 s11, s11, 2
	s_or_b32 s11, s11, 3
	s_cmp_ge_u32 s11, s32
	s_cbranch_scc1 .Lgb0_done
	s_add_i32 s10, s10, 1
	s_cmp_gt_u32 s10, 0x2000
	s_cbranch_scc1 .Lgb0_done
	s_sleep 1
	s_branch .Lgb0_spin
.Lgb0_done:
	buffer_inv sc1
	s_waitcnt vmcnt(0)
.Lgb0_join:
	s_or_b64 exec, exec, s[4:5]
	s_barrier
	s_branch .LBB0_338
.Lgb0_slow:
	s_mov_b64 s[8:9], s[0:1]
	s_mov_b32 s40, s90
	s_waitcnt vmcnt(0)
	s_barrier
	s_mov_b64 s[4:5], exec
	v_readlane_b32 s10, v255, 5
	v_readlane_b32 s11, v255, 6
	s_and_b64 s[10:11], s[4:5], s[10:11]
	s_mov_b64 exec, s[10:11]
	s_cbranch_execz .LBB0_337
	v_readlane_b32 s10, v255, 16
	s_load_dwordx2 s[8:9], s[8:9], 0xd8
	s_waitcnt vmcnt(0) expcnt(0) lgkmcnt(0)
	v_mov_b32_e32 v2, s10
	ds_read_b32 v5, v2
	v_readlane_b32 s10, v255, 17
	s_waitcnt lgkmcnt(0)
	v_cmp_ne_u32_e32 vcc, 0, v5
	v_mov_b32_e32 v2, s10
	ds_read_b32 v4, v2
	s_cbranch_vccnz .LBB0_301
	v_readlane_b32 s10, v255, 2
	v_readlane_b32 s11, v255, 3
	s_load_dwordx2 s[18:19], s[10:11], 0x4
	s_add_u32 s10, s8, 0x4200
	s_addc_u32 s11, s9, 0
	s_add_u32 s14, s8, 0x4400
	s_addc_u32 s15, s9, 0
	s_waitcnt lgkmcnt(0)
	s_mul_i32 s35, s18, s65
	s_add_u32 s18, s8, 0x4500
	s_mul_i32 s35, s35, s19
	s_addc_u32 s19, s9, 0
	s_add_u32 s20, s8, 0x4600
	s_addc_u32 s21, s9, 0
	s_add_u32 s22, s8, 0x4700
	s_addc_u32 s23, s9, 0
	s_add_u32 s24, s8, 0x4800
	s_addc_u32 s25, s9, 0
	s_add_u32 s26, s8, 0x4900
	s_addc_u32 s27, s9, 0
	s_add_u32 s28, s8, 0x4a00
	s_addc_u32 s29, s9, 0
	s_add_u32 s30, s8, 0x4b00
	s_addc_u32 s31, s9, 0
	s_add_u32 s36, s8, 0x4c00
	s_addc_u32 s37, s9, 0
	s_add_u32 s44, s8, 0x4d00
	s_addc_u32 s45, s9, 0
	s_add_u32 s46, s8, 0x4e00
	s_addc_u32 s47, s9, 0
	s_add_u32 s72, s8, 0x4f00
	s_addc_u32 s73, s9, 0
	s_add_u32 s74, s8, 0x5000
	s_addc_u32 s75, s9, 0
	s_add_u32 s76, s8, 0x5100
	s_addc_u32 s77, s9, 0
	s_add_u32 s78, s8, 0x5200
	s_addc_u32 s79, s9, 0
	s_add_u32 s82, s8, 0x5300
	s_addc_u32 s83, s9, 0
	s_mov_b32 s48, 1
	s_branch .LBB0_289

.LBB0_337:
	s_or_b64 exec, exec, s[4:5]
	s_waitcnt lgkmcnt(0)
	s_barrier
	s_load_dwordx2 s[8:9], s[0:1], 0xd8
	v_mov_b32_e32 v248, 0
	s_waitcnt lgkmcnt(0)
	s_add_u32 s8, s8, 0x20000
	s_addc_u32 s9, s9, 0
	global_load_dword v250, v248, s[8:9] sc1
	s_waitcnt vmcnt(0)
	v_readfirstlane_b32 s10, v250
	s_nop 3
	s_cmp_eq_u32 s10, 0
	s_cselect_b32 s10, 1, 0
	s_or_b32 s32, s32, s10

.LBB0_359:
	v_readlane_b32 s4, v255, 15
	s_add_i32 s34, s4, 2
	v_readlane_b32 s4, v255, 0
	v_readlane_b32 s5, v255, 1
	s_cmp_ge_i32 s34, s5
	s_cbranch_scc1 .LBB0_413
	s_bitcmp0_b32 s32, 0
	s_cbranch_scc1 .Lgb1_slow
	s_waitcnt vmcnt(0)
	s_barrier
	s_add_i32 s32, s32, 16
	v_cmp_eq_u32_e32 vcc, 0, v0
	s_and_saveexec_b64 s[4:5], vcc
	s_cbranch_execz .Lgb1_join
	s_load_dwordx2 s[8:9], s[0:1], 0xd8
	s_and_b32 s11, s87, 63
	s_lshl_b32 s11, s11, 8
	v_mov_b32_e32 v248, 0
	v_mov_b32_e32 v249, 1
	s_mov_b32 s10, 0
	s_waitcnt lgkmcnt(0)
	s_add_u32 s8, s8, s11
	s_addc_u32 s9, s9, 0
	s_add_u32 s8, s8, 0x10000
	s_addc_u32 s9, s9, 0
	global_atomic_add v248, v249, s[8:9]

.Lgb1_slow:
	s_mov_b64 s[8:9], s[0:1]
	s_mov_b32 s40, s90
	s_waitcnt vmcnt(0)
	s_waitcnt vmcnt(0)
	s_barrier
	s_mov_b64 s[4:5], exec
	v_readlane_b32 s10, v255, 5
	v_readlane_b32 s11, v255, 6
	s_and_b64 s[10:11], s[4:5], s[10:11]
	s_mov_b64 exec, s[10:11]
	s_cbranch_execz .LBB0_412
	v_readlane_b32 s10, v255, 16
	s_load_dwordx2 s[8:9], s[8:9], 0xd8
	s_waitcnt vmcnt(0) expcnt(0) lgkmcnt(0)
	v_mov_b32_e32 v2, s10
	ds_read_b32 v5, v2
	v_readlane_b32 s10, v255, 17
	s_waitcnt lgkmcnt(0)
	v_cmp_ne_u32_e32 vcc, 0, v5
	v_mov_b32_e32 v2, s10
	ds_read_b32 v4, v2
	s_cbranch_vccnz .LBB0_376
	v_readlane_b32 s10, v255, 2
	v_readlane_b32 s11, v255, 3
	s_load_dwordx2 s[18:19], s[10:11], 0x4
	s_add_u32 s10, s8, 0x4200
	s_addc_u32 s11, s9, 0
	s_add_u32 s14, s8, 0x4400
	s_addc_u32 s15, s9, 0
	s_waitcnt lgkmcnt(0)
	s_mul_i32 s35, s18, s65
	s_add_u32 s18, s8, 0x4500
	s_mul_i32 s35, s35, s19
	s_addc_u32 s19, s9, 0
	s_add_u32 s20, s8, 0x4600
	s_addc_u32 s21, s9, 0
	s_add_u32 s22, s8, 0x4700
	s_addc_u32 s23, s9, 0
	s_add_u32 s24, s8, 0x4800
	s_addc_u32 s25, s9, 0
	s_add_u32 s26, s8, 0x4900
	s_addc_u32 s27, s9, 0
	s_add_u32 s28, s8, 0x4a00
	s_addc_u32 s29, s9, 0
	s_add_u32 s30, s8, 0x4b00
	s_addc_u32 s31, s9, 0
	s_add_u32 s36, s8, 0x4c00
	s_addc_u32 s37, s9, 0
	s_add_u32 s44, s8, 0x4d00
	s_addc_u32 s45, s9, 0
	s_add_u32 s46, s8, 0x4e00
	s_addc_u32 s47, s9, 0
	s_add_u32 s72, s8, 0x4f00
	s_addc_u32 s73, s9, 0
	s_add_u32 s74, s8, 0x5000
	s_addc_u32 s75, s9, 0
	s_add_u32 s76, s8, 0x5100
	s_addc_u32 s77, s9, 0
	s_add_u32 s78, s8, 0x5200
	s_addc_u32 s79, s9, 0
	s_add_u32 s82, s8, 0x5300
	s_addc_u32 s83, s9, 0
	s_mov_b32 s48, 1
	s_branch .LBB0_364

.LBB0_442:
	v_readlane_b32 s4, v255, 15
	s_add_i32 s34, s4, 3
	v_readlane_b32 s4, v255, 0
	v_readlane_b32 s5, v255, 1
	s_cmp_ge_i32 s34, s5
	s_cbranch_scc1 .LBB0_496
	s_bitcmp0_b32 s32, 0
	s_cbranch_scc1 .Lgb2_slow
	s_cmp_eq_u32 s34, 25
	s_cbranch_scc1 .Lgb2_slow
	s_waitcnt vmcnt(0)
	s_barrier
	s_add_i32 s32, s32, 16
	v_cmp_eq_u32_e32 vcc, 0, v0
	s_and_saveexec_b64 s[4:5], vcc
	s_cbranch_execz .Lgb2_join
	s_load_dwordx2 s[8:9], s[0:1], 0xd8
	s_and_b32 s11, s87, 63
	s_lshl_b32 s11, s11, 8
	v_mov_b32_e32 v248, 0
	v_mov_b32_e32 v249, 1
	s_mov_b32 s10, 0
	s_waitcnt lgkmcnt(0)
	s_add_u32 s8, s8, s11
	s_addc_u32 s9, s9, 0
	s_add_u32 s8, s8, 0x10000
	s_addc_u32 s9, s9, 0
	global_atomic_add v248, v249, s[8:9]

.Lgb2_slow:
	s_mov_b64 s[8:9], s[0:1]
	s_mov_b32 s40, s90
	s_waitcnt vmcnt(0)
	s_waitcnt vmcnt(0)
	s_barrier
	s_mov_b64 s[4:5], exec
	v_readlane_b32 s10, v255, 5
	v_readlane_b32 s11, v255, 6
	s_and_b64 s[10:11], s[4:5], s[10:11]
	s_mov_b64 exec, s[10:11]
	s_cbranch_execz .LBB0_495
	v_readlane_b32 s10, v255, 16
	s_load_dwordx2 s[8:9], s[8:9], 0xd8
	s_waitcnt vmcnt(0) expcnt(0) lgkmcnt(0)
	v_mov_b32_e32 v2, s10
	ds_read_b32 v5, v2
	v_readlane_b32 s10, v255, 17
	s_waitcnt lgkmcnt(0)
	v_cmp_ne_u32_e32 vcc, 0, v5
	v_mov_b32_e32 v2, s10
	ds_read_b32 v4, v2
	s_cbranch_vccnz .LBB0_459
	v_readlane_b32 s10, v255, 2
	v_readlane_b32 s11, v255, 3
	s_load_dwordx2 s[18:19], s[10:11], 0x4
	s_add_u32 s10, s8, 0x4200
	s_addc_u32 s11, s9, 0
	s_add_u32 s14, s8, 0x4400
	s_addc_u32 s15, s9, 0
	s_waitcnt lgkmcnt(0)
	s_mul_i32 s17, s18, s65
	s_add_u32 s18, s8, 0x4500
	s_mul_i32 s17, s17, s19
	s_addc_u32 s19, s9, 0
	s_add_u32 s20, s8, 0x4600
	s_addc_u32 s21, s9, 0
	s_add_u32 s22, s8, 0x4700
	s_addc_u32 s23, s9, 0
	s_add_u32 s24, s8, 0x4800
	s_addc_u32 s25, s9, 0
	s_add_u32 s26, s8, 0x4900
	s_addc_u32 s27, s9, 0
	s_add_u32 s28, s8, 0x4a00
	s_addc_u32 s29, s9, 0
	s_add_u32 s30, s8, 0x4b00
	s_addc_u32 s31, s9, 0
	s_add_u32 s36, s8, 0x4c00
	s_addc_u32 s37, s9, 0
	s_add_u32 s44, s8, 0x4d00
	s_addc_u32 s45, s9, 0
	s_add_u32 s46, s8, 0x4e00
	s_addc_u32 s47, s9, 0
	s_add_u32 s72, s8, 0x4f00
	s_addc_u32 s73, s9, 0
	s_add_u32 s74, s8, 0x5000
	s_addc_u32 s75, s9, 0
	s_add_u32 s76, s8, 0x5100
	s_addc_u32 s77, s9, 0
	s_add_u32 s78, s8, 0x5200
	s_addc_u32 s79, s9, 0
	s_add_u32 s82, s8, 0x5300
	s_addc_u32 s83, s9, 0
	s_mov_b32 s35, 1
	s_branch .LBB0_447

.Lgb3_after:
	s_getpc_b64 s[98:99]

.LBB0_1221:
	s_bitcmp0_b32 s32, 0
	s_cbranch_scc1 .Lgb3_slow
	s_waitcnt vmcnt(0)
	s_barrier
	s_add_i32 s32, s32, 16
	v_cmp_eq_u32_e32 vcc, 0, v0
	s_and_saveexec_b64 s[4:5], vcc
	s_cbranch_execz .Lgb3_join
	s_load_dwordx2 s[8:9], s[0:1], 0xd8
	s_and_b32 s11, s87, 63
	s_lshl_b32 s11, s11, 8
	v_mov_b32_e32 v248, 0
	v_mov_b32_e32 v249, 1
	s_mov_b32 s10, 0
	s_waitcnt lgkmcnt(0)
	s_add_u32 s8, s8, s11
	s_addc_u32 s9, s9, 0
	s_add_u32 s8, s8, 0x10000
	s_addc_u32 s9, s9, 0
	global_atomic_add v248, v249, s[8:9]
